# v5 + stick-breaking clamp/exp instruction selection: canonicalizing v_max dropped, min+exp de-serialized over 8 rotating temps (bit-identical)
# baseline (speedup 1.0000x reference)
.LBB0_915:
	s_cmp_lt_i32 s16, 0
	s_cselect_b64 s[18:19], -1, 0
	s_or_b64 s[18:19], s[0:1], s[18:19]
	s_cmp_gt_i32 s31, s33
	s_cselect_b64 s[44:45], -1, 0
	s_or_b64 s[18:19], s[18:19], s[44:45]
	s_and_b64 vcc, exec, s[18:19]
	s_cbranch_vccnz .LBB0_921
	v_mov_b32_e32 v154, v143
	s_add_i32 s0, s31, 63
	v_add_u32_e32 v86, v145, v154
	ds_read_b128 v[82:85], v86 offset:32768
	ds_read_b128 v[98:101], v86 offset:40960
	v_xad_u32 v150, v154, 32, v145
	s_waitcnt lgkmcnt(0)
	v_mfma_f32_32x32x16_bf16 v[82:97], v[82:85], v[4:7], 0
	ds_read_b128 v[146:149], v150 offset:32768
	ds_read_b128 v[150:153], v150 offset:40960
	v_xad_u32 v155, v154, 64, v145
	s_cmp_lt_i32 s0, s8
	v_mfma_f32_32x32x16_bf16 v[98:113], v[98:101], v[4:7], 0
	s_waitcnt lgkmcnt(0)
	v_mfma_f32_32x32x16_bf16 v[82:97], v[146:149], v[8:11], v[82:97]
	v_mfma_f32_32x32x16_bf16 v[98:113], v[150:153], v[8:11], v[98:113]
	ds_read_b128 v[146:149], v155 offset:32768
	ds_read_b128 v[150:153], v155 offset:40960
	v_xad_u32 v155, v154, s56, v145
	s_waitcnt lgkmcnt(0)
	v_mfma_f32_32x32x16_bf16 v[82:97], v[146:149], v[12:15], v[82:97]
	v_mfma_f32_32x32x16_bf16 v[98:113], v[150:153], v[12:15], v[98:113]
	ds_read_b128 v[146:149], v155 offset:32768
	ds_read_b128 v[150:153], v155 offset:40960
	v_xad_u32 v155, v154, s90, v145
	s_waitcnt lgkmcnt(0)
	v_mfma_f32_32x32x16_bf16 v[82:97], v[146:149], v[114:117], v[82:97]
	v_mfma_f32_32x32x16_bf16 v[98:113], v[150:153], v[114:117], v[98:113]
	ds_read_b128 v[146:149], v155 offset:32768
	ds_read_b128 v[150:153], v155 offset:40960
	v_xad_u32 v155, v154, s91, v145
	s_waitcnt lgkmcnt(0)
	v_mfma_f32_32x32x16_bf16 v[82:97], v[146:149], v[118:121], v[82:97]
	v_mfma_f32_32x32x16_bf16 v[98:113], v[150:153], v[118:121], v[98:113]
	ds_read_b128 v[146:149], v155 offset:32768
	ds_read_b128 v[150:153], v155 offset:40960
	v_xad_u32 v155, v154, s57, v145
	v_xad_u32 v154, v154, s28, v145
	s_waitcnt lgkmcnt(0)
	v_mfma_f32_32x32x16_bf16 v[82:97], v[146:149], v[122:125], v[82:97]
	v_mfma_f32_32x32x16_bf16 v[98:113], v[150:153], v[122:125], v[98:113]
	ds_read_b128 v[146:149], v155 offset:32768
	ds_read_b128 v[150:153], v155 offset:40960
	s_waitcnt lgkmcnt(0)
	v_mfma_f32_32x32x16_bf16 v[82:97], v[146:149], v[126:129], v[82:97]
	v_mfma_f32_32x32x16_bf16 v[98:113], v[150:153], v[126:129], v[98:113]
	ds_read_b128 v[146:149], v154 offset:32768
	ds_read_b128 v[150:153], v154 offset:40960
	s_waitcnt lgkmcnt(0)
	v_mfma_f32_32x32x16_bf16 v[82:97], v[146:149], v[130:133], v[82:97]
	v_mfma_f32_32x32x16_bf16 v[98:113], v[150:153], v[130:133], v[98:113]
	s_nop 10
	v_min_f32_e32 v213, 0x42fc0000, v82
	v_min_f32_e32 v214, 0x42fc0000, v83
	v_min_f32_e32 v215, 0x42fc0000, v98
	v_min_f32_e32 v216, 0x42fc0000, v99
	v_exp_f32_e32 v162, v213
	v_exp_f32_e32 v163, v214
	v_exp_f32_e32 v164, v215
	v_exp_f32_e32 v165, v216
	v_min_f32_e32 v217, 0x42fc0000, v84
	v_min_f32_e32 v218, 0x42fc0000, v100
	v_min_f32_e32 v219, 0x42fc0000, v85
	v_min_f32_e32 v220, 0x42fc0000, v101
	v_exp_f32_e32 v166, v217
	v_exp_f32_e32 v180, v218
	v_exp_f32_e32 v167, v219
	v_exp_f32_e32 v181, v220
	v_min_f32_e32 v213, 0x42fc0000, v86
	v_min_f32_e32 v214, 0x42fc0000, v102
	v_min_f32_e32 v215, 0x42fc0000, v87
	v_min_f32_e32 v216, 0x42fc0000, v103
	v_exp_f32_e32 v148, v213
	v_exp_f32_e32 v170, v214
	v_exp_f32_e32 v149, v215
	v_exp_f32_e32 v171, v216
	v_min_f32_e32 v217, 0x42fc0000, v88
	v_min_f32_e32 v218, 0x42fc0000, v104
	v_min_f32_e32 v219, 0x42fc0000, v89
	v_min_f32_e32 v220, 0x42fc0000, v105
	v_exp_f32_e32 v168, v217
	v_exp_f32_e32 v182, v218
	v_exp_f32_e32 v169, v219
	v_exp_f32_e32 v183, v220
	v_min_f32_e32 v213, 0x42fc0000, v90
	v_min_f32_e32 v214, 0x42fc0000, v106
	v_min_f32_e32 v215, 0x42fc0000, v91
	v_min_f32_e32 v216, 0x42fc0000, v107
	v_exp_f32_e32 v150, v213
	v_exp_f32_e32 v172, v214
	v_exp_f32_e32 v151, v215
	v_exp_f32_e32 v173, v216
	v_min_f32_e32 v217, 0x42fc0000, v92
	v_min_f32_e32 v218, 0x42fc0000, v108
	v_min_f32_e32 v219, 0x42fc0000, v93
	v_min_f32_e32 v220, 0x42fc0000, v109
	v_exp_f32_e32 v106, v217
	v_exp_f32_e32 v184, v218
	v_exp_f32_e32 v107, v219
	v_exp_f32_e32 v185, v220
	v_min_f32_e32 v213, 0x42fc0000, v94
	v_min_f32_e32 v214, 0x42fc0000, v110
	v_min_f32_e32 v215, 0x42fc0000, v95
	v_min_f32_e32 v216, 0x42fc0000, v111
	v_exp_f32_e32 v108, v213
	v_exp_f32_e32 v176, v214
	v_exp_f32_e32 v109, v215
	v_exp_f32_e32 v177, v216
	v_min_f32_e32 v217, 0x42fc0000, v96
	v_min_f32_e32 v218, 0x42fc0000, v112
	v_min_f32_e32 v219, 0x42fc0000, v97
	v_min_f32_e32 v220, 0x42fc0000, v113
	v_exp_f32_e32 v110, v217
	v_exp_f32_e32 v174, v218
	v_exp_f32_e32 v111, v219
	v_exp_f32_e32 v175, v220
	v_add_f32_e32 v83, 1.0, v164
	v_add_f32_e32 v84, 1.0, v165
	v_add_f32_e32 v85, 1.0, v180
	v_add_f32_e32 v86, 1.0, v181
	v_add_f32_e32 v87, 1.0, v170
	v_add_f32_e32 v88, 1.0, v171
	v_add_f32_e32 v89, 1.0, v182
	v_add_f32_e32 v92, 1.0, v183
	v_add_f32_e32 v93, 1.0, v172
	v_add_f32_e32 v96, 1.0, v173
	v_add_f32_e32 v97, 1.0, v184
	v_add_f32_e32 v100, 1.0, v185
	v_add_f32_e32 v101, 1.0, v176
	v_add_f32_e32 v104, 1.0, v177
	v_add_f32_e32 v112, 1.0, v174
	v_add_f32_e32 v82, 1.0, v162
	v_rcp_f32_e32 v90, v83
	v_add_f32_e32 v83, 1.0, v163
	v_rcp_f32_e32 v91, v84
	v_add_f32_e32 v84, 1.0, v166
	v_rcp_f32_e32 v94, v85
	v_add_f32_e32 v85, 1.0, v167
	v_rcp_f32_e32 v95, v86
	v_add_f32_e32 v86, 1.0, v148
	v_rcp_f32_e32 v98, v87
	v_add_f32_e32 v87, 1.0, v149
	v_rcp_f32_e32 v99, v88
	v_add_f32_e32 v88, 1.0, v168
	v_rcp_f32_e32 v102, v89
	v_add_f32_e32 v89, 1.0, v169
	v_rcp_f32_e32 v103, v92
	v_add_f32_e32 v92, 1.0, v150
	v_rcp_f32_e32 v146, v93
	v_add_f32_e32 v93, 1.0, v151
	v_rcp_f32_e32 v147, v96
	v_add_f32_e32 v96, 1.0, v106
	v_rcp_f32_e32 v156, v97
	v_add_f32_e32 v97, 1.0, v107
	v_rcp_f32_e32 v157, v100
	v_add_f32_e32 v100, 1.0, v108
	v_rcp_f32_e32 v158, v101
	v_add_f32_e32 v101, 1.0, v109
	v_rcp_f32_e32 v159, v104
	v_add_f32_e32 v104, 1.0, v110
	v_add_f32_e32 v105, 1.0, v111
	v_rcp_f32_e32 v160, v112
	v_add_f32_e32 v112, 1.0, v175
	v_rcp_f32_e32 v82, v82
	v_rcp_f32_e32 v83, v83
	v_rcp_f32_e32 v84, v84
	v_rcp_f32_e32 v85, v85
	v_rcp_f32_e32 v86, v86
	v_rcp_f32_e32 v87, v87
	v_rcp_f32_e32 v88, v88
	v_rcp_f32_e32 v89, v89
	v_rcp_f32_e32 v92, v92
	v_rcp_f32_e32 v93, v93
	v_rcp_f32_e32 v96, v96
	v_rcp_f32_e32 v97, v97
	v_rcp_f32_e32 v100, v100
	v_rcp_f32_e32 v101, v101
	v_rcp_f32_e32 v104, v104
	v_rcp_f32_e32 v105, v105
	v_rcp_f32_e32 v161, v112
	v_pk_mul_f32 v[154:155], v[108:109], v[100:101]
	v_pk_mul_f32 v[112:113], v[106:107], v[96:97]
	v_pk_mul_f32 v[152:153], v[110:111], v[104:105]
	v_pk_mul_f32 v[150:151], v[150:151], v[92:93]
	v_pk_mul_f32 v[110:111], v[168:169], v[88:89]
	v_pk_mul_f32 v[148:149], v[148:149], v[86:87]
	v_pk_mul_f32 v[106:107], v[166:167], v[84:85]
	v_pk_mul_f32 v[108:109], v[162:163], v[82:83]
	v_pk_mul_f32 v[174:175], v[174:175], v[160:161]
	v_pk_mul_f32 v[176:177], v[176:177], v[158:159]
	v_pk_mul_f32 v[168:169], v[184:185], v[156:157]
	v_pk_mul_f32 v[172:173], v[172:173], v[146:147]
	v_pk_mul_f32 v[166:167], v[182:183], v[102:103]
	v_pk_mul_f32 v[170:171], v[170:171], v[98:99]
	v_pk_mul_f32 v[162:163], v[180:181], v[94:95]
	v_pk_mul_f32 v[164:165], v[164:165], v[90:91]
	s_cbranch_scc1 .LBB0_920
	v_add_u32_e32 v180, 0x4000003b, v192
	s_brev_b32 s0, -4
	v_cmp_lt_u32_e32 vcc, s0, v180
	v_add_u32_e32 v180, 27, v192
	v_cmp_gt_u32_e64 s[0:1], -2.0, v180
	v_add_u32_e32 v180, 58, v192
	v_cmp_gt_u32_e64 s[44:45], -2.0, v180
	v_add_u32_e32 v180, 26, v192
	v_cndmask_b32_e64 v90, v90, 0, s[0:1]
	v_cndmask_b32_e64 v164, v164, 1.0, s[0:1]
	v_cmp_gt_u32_e64 s[0:1], -2.0, v180
	v_add_u32_e32 v180, 57, v192
	v_cmp_gt_u32_e64 s[46:47], -2.0, v180
	v_add_u32_e32 v180, 25, v192
	v_cndmask_b32_e64 v91, v91, 0, s[0:1]
	v_cndmask_b32_e64 v165, v165, 1.0, s[0:1]
	v_cmp_gt_u32_e64 s[0:1], -2.0, v180
	v_add_u32_e32 v180, 56, v192
	v_cmp_gt_u32_e64 s[48:49], -2.0, v180
	v_add_u32_e32 v180, 24, v192
	v_cndmask_b32_e64 v94, v94, 0, s[0:1]
	v_cndmask_b32_e64 v162, v162, 1.0, s[0:1]
	v_cmp_gt_u32_e64 s[0:1], -2.0, v180
	v_add_u32_e32 v180, 51, v192
	v_cmp_gt_u32_e64 s[50:51], -2.0, v180
	v_add_u32_e32 v180, 19, v192
	v_cndmask_b32_e64 v95, v95, 0, s[0:1]
	v_cndmask_b32_e64 v163, v163, 1.0, s[0:1]
	v_cmp_gt_u32_e64 s[0:1], -2.0, v180
	v_add_u32_e32 v180, 50, v192
	v_cmp_gt_u32_e64 s[52:53], -2.0, v180
	v_add_u32_e32 v180, 18, v192
	v_cndmask_b32_e64 v98, v98, 0, s[0:1]
	v_cndmask_b32_e64 v170, v170, 1.0, s[0:1]
	v_cmp_gt_u32_e64 s[0:1], -2.0, v180
	v_add_u32_e32 v180, 49, v192
	v_cmp_gt_u32_e64 s[54:55], -2.0, v180
	v_add_u32_e32 v180, 17, v192
	v_cndmask_b32_e64 v99, v99, 0, s[0:1]
	v_cndmask_b32_e64 v171, v171, 1.0, s[0:1]
	v_cmp_gt_u32_e64 s[0:1], -2.0, v180
	v_add_u32_e32 v180, 48, v192
	v_cmp_gt_u32_e64 s[76:77], -2.0, v192
	v_cndmask_b32_e64 v102, v102, 0, s[0:1]
	v_cndmask_b32_e64 v166, v166, 1.0, s[0:1]
	v_cmp_gt_u32_e64 s[0:1], -2.0, v180
	v_add_u32_e32 v180, 16, v192
	v_cmp_gt_u32_e64 s[58:59], -2.0, v180
	v_add_u32_e32 v180, 43, v192
	s_nop 0
	v_cndmask_b32_e64 v103, v103, 0, s[58:59]
	v_cndmask_b32_e64 v167, v167, 1.0, s[58:59]
	v_cmp_gt_u32_e64 s[58:59], -2.0, v180
	v_add_u32_e32 v180, 11, v192
	v_cmp_gt_u32_e64 s[60:61], -2.0, v180
	v_add_u32_e32 v180, 42, v192
	s_nop 0
	v_cndmask_b32_e64 v146, v146, 0, s[60:61]
	v_cndmask_b32_e64 v172, v172, 1.0, s[60:61]
	v_cmp_gt_u32_e64 s[60:61], -2.0, v180
	v_add_u32_e32 v180, 10, v192
	v_cmp_gt_u32_e64 s[62:63], -2.0, v180
	v_add_u32_e32 v180, 41, v192
	s_nop 0
	v_cndmask_b32_e64 v147, v147, 0, s[62:63]
	v_cndmask_b32_e64 v173, v173, 1.0, s[62:63]
	v_cmp_gt_u32_e64 s[62:63], -2.0, v180
	v_add_u32_e32 v180, 9, v192
	v_cmp_gt_u32_e64 s[64:65], -2.0, v180
	v_add_u32_e32 v180, 40, v192
	s_nop 0
	v_cndmask_b32_e64 v156, v156, 0, s[64:65]
	v_cndmask_b32_e64 v168, v168, 1.0, s[64:65]
	v_cmp_gt_u32_e64 s[64:65], -2.0, v180
	v_add_u32_e32 v180, 8, v192
	v_cmp_gt_u32_e64 s[66:67], -2.0, v180
	v_add_u32_e32 v180, 35, v192
	s_nop 0
	v_cndmask_b32_e64 v157, v157, 0, s[66:67]
	v_cndmask_b32_e64 v169, v169, 1.0, s[66:67]
	v_cmp_gt_u32_e64 s[66:67], -2.0, v180
	v_add_u32_e32 v180, 3, v192
	v_cmp_gt_u32_e64 s[68:69], -2.0, v180
	v_add_u32_e32 v180, 34, v192
	s_nop 0
	v_cndmask_b32_e64 v158, v158, 0, s[68:69]
	v_cndmask_b32_e64 v176, v176, 1.0, s[68:69]
	v_cmp_gt_u32_e64 s[68:69], -2.0, v180
	v_add_u32_e32 v180, 2, v192
	v_cmp_gt_u32_e64 s[70:71], -2.0, v180
	v_add_u32_e32 v180, 33, v192
	s_nop 0
	v_cndmask_b32_e64 v159, v159, 0, s[70:71]
	v_cndmask_b32_e64 v177, v177, 1.0, s[70:71]
	v_cmp_gt_u32_e64 s[70:71], -2.0, v180
	v_add_u32_e32 v180, 1, v192
	v_cmp_gt_u32_e64 s[72:73], -2.0, v180
	v_add_u32_e32 v180, 32, v192
	s_nop 0
	v_cndmask_b32_e64 v160, v160, 0, s[72:73]
	v_cndmask_b32_e64 v174, v174, 1.0, s[72:73]
	v_cmp_gt_u32_e64 s[72:73], -2.0, v180
	s_and_saveexec_b64 s[18:19], s[76:77]
	s_mov_b32 s25, 1.0
	v_mov_b32_e32 v175, s25
	v_mov_b32_e32 v161, 0
	s_or_b64 exec, exec, s[18:19]
	v_cndmask_b32_e64 v82, v82, 0, vcc
	v_cndmask_b32_e64 v108, v108, 1.0, vcc
	v_cndmask_b32_e64 v83, v83, 0, s[44:45]
	v_cndmask_b32_e64 v109, v109, 1.0, s[44:45]
	v_cndmask_b32_e64 v84, v84, 0, s[46:47]
	v_cndmask_b32_e64 v106, v106, 1.0, s[46:47]
	v_cndmask_b32_e64 v85, v85, 0, s[48:49]
	v_cndmask_b32_e64 v107, v107, 1.0, s[48:49]
	v_cndmask_b32_e64 v86, v86, 0, s[50:51]
	v_cndmask_b32_e64 v148, v148, 1.0, s[50:51]
	v_cndmask_b32_e64 v87, v87, 0, s[52:53]
	v_cndmask_b32_e64 v149, v149, 1.0, s[52:53]
	v_cndmask_b32_e64 v88, v88, 0, s[54:55]
	v_cndmask_b32_e64 v110, v110, 1.0, s[54:55]
	v_cndmask_b32_e64 v89, v89, 0, s[0:1]
	v_cndmask_b32_e64 v111, v111, 1.0, s[0:1]
	v_cndmask_b32_e64 v92, v92, 0, s[58:59]
	v_cndmask_b32_e64 v150, v150, 1.0, s[58:59]
	v_cndmask_b32_e64 v93, v93, 0, s[60:61]
	v_cndmask_b32_e64 v151, v151, 1.0, s[60:61]
	v_cndmask_b32_e64 v96, v96, 0, s[62:63]
	v_cndmask_b32_e64 v112, v112, 1.0, s[62:63]
	v_cndmask_b32_e64 v97, v97, 0, s[64:65]
	v_cndmask_b32_e64 v113, v113, 1.0, s[64:65]
	v_cndmask_b32_e64 v100, v100, 0, s[66:67]
	v_cndmask_b32_e64 v154, v154, 1.0, s[66:67]
	v_cndmask_b32_e64 v101, v101, 0, s[68:69]
	v_cndmask_b32_e64 v155, v155, 1.0, s[68:69]
	v_cndmask_b32_e64 v104, v104, 0, s[70:71]
	v_cndmask_b32_e64 v152, v152, 1.0, s[70:71]
	v_cndmask_b32_e64 v105, v105, 0, s[72:73]
	v_cndmask_b32_e64 v153, v153, 1.0, s[72:73]
	v_readlane_b32 s48, v254, 46

.LBB0_927:
	s_sub_i32 s44, s31, 64
	s_cmp_lt_i32 s25, 0
	s_cselect_b64 s[18:19], -1, 0
	s_or_b64 s[18:19], s[18:19], s[0:1]
	s_cmp_gt_i32 s44, s33
	s_cselect_b64 s[44:45], -1, 0
	s_or_b64 s[18:19], s[18:19], s[44:45]
	s_and_b64 vcc, exec, s[18:19]
	s_cbranch_vccnz .LBB0_933
	v_mov_b32_e32 v154, v143
	s_add_i32 s0, s31, -1
	v_add_u32_e32 v86, v145, v154
	ds_read_b128 v[82:85], v86 offset:49152
	ds_read_b128 v[98:101], v86 offset:57344
	v_xad_u32 v150, v154, 32, v145
	s_waitcnt lgkmcnt(0)
	v_mfma_f32_32x32x16_bf16 v[82:97], v[82:85], v[4:7], 0
	ds_read_b128 v[146:149], v150 offset:49152
	ds_read_b128 v[150:153], v150 offset:57344
	v_xad_u32 v155, v154, 64, v145
	s_cmp_lt_i32 s0, s8
	v_mfma_f32_32x32x16_bf16 v[98:113], v[98:101], v[4:7], 0
	s_waitcnt lgkmcnt(0)
	v_mfma_f32_32x32x16_bf16 v[82:97], v[146:149], v[8:11], v[82:97]
	v_mfma_f32_32x32x16_bf16 v[98:113], v[150:153], v[8:11], v[98:113]
	ds_read_b128 v[146:149], v155 offset:49152
	ds_read_b128 v[150:153], v155 offset:57344
	v_xad_u32 v155, v154, s56, v145
	s_waitcnt lgkmcnt(0)
	v_mfma_f32_32x32x16_bf16 v[82:97], v[146:149], v[12:15], v[82:97]
	v_mfma_f32_32x32x16_bf16 v[98:113], v[150:153], v[12:15], v[98:113]
	ds_read_b128 v[146:149], v155 offset:49152
	ds_read_b128 v[150:153], v155 offset:57344
	v_xad_u32 v155, v154, s90, v145
	s_waitcnt lgkmcnt(0)
	v_mfma_f32_32x32x16_bf16 v[82:97], v[146:149], v[114:117], v[82:97]
	v_mfma_f32_32x32x16_bf16 v[98:113], v[150:153], v[114:117], v[98:113]
	ds_read_b128 v[146:149], v155 offset:49152
	ds_read_b128 v[150:153], v155 offset:57344
	v_xad_u32 v155, v154, s91, v145
	s_waitcnt lgkmcnt(0)
	v_mfma_f32_32x32x16_bf16 v[82:97], v[146:149], v[118:121], v[82:97]
	v_mfma_f32_32x32x16_bf16 v[98:113], v[150:153], v[118:121], v[98:113]
	ds_read_b128 v[146:149], v155 offset:49152
	ds_read_b128 v[150:153], v155 offset:57344
	v_xad_u32 v155, v154, s57, v145
	v_xad_u32 v154, v154, s28, v145
	s_waitcnt lgkmcnt(0)
	v_mfma_f32_32x32x16_bf16 v[82:97], v[146:149], v[122:125], v[82:97]
	v_mfma_f32_32x32x16_bf16 v[98:113], v[150:153], v[122:125], v[98:113]
	ds_read_b128 v[146:149], v155 offset:49152
	ds_read_b128 v[150:153], v155 offset:57344
	s_waitcnt lgkmcnt(0)
	v_mfma_f32_32x32x16_bf16 v[82:97], v[146:149], v[126:129], v[82:97]
	v_mfma_f32_32x32x16_bf16 v[98:113], v[150:153], v[126:129], v[98:113]
	ds_read_b128 v[146:149], v154 offset:49152
	ds_read_b128 v[150:153], v154 offset:57344
	s_waitcnt lgkmcnt(0)
	v_mfma_f32_32x32x16_bf16 v[82:97], v[146:149], v[130:133], v[82:97]
	v_mfma_f32_32x32x16_bf16 v[98:113], v[150:153], v[130:133], v[98:113]
	s_nop 10
	v_min_f32_e32 v213, 0x42fc0000, v82
	v_min_f32_e32 v214, 0x42fc0000, v83
	v_min_f32_e32 v215, 0x42fc0000, v98
	v_min_f32_e32 v216, 0x42fc0000, v99
	v_exp_f32_e32 v162, v213
	v_exp_f32_e32 v163, v214
	v_exp_f32_e32 v164, v215
	v_exp_f32_e32 v165, v216
	v_min_f32_e32 v217, 0x42fc0000, v84
	v_min_f32_e32 v218, 0x42fc0000, v100
	v_min_f32_e32 v219, 0x42fc0000, v85
	v_min_f32_e32 v220, 0x42fc0000, v101
	v_exp_f32_e32 v166, v217
	v_exp_f32_e32 v180, v218
	v_exp_f32_e32 v167, v219
	v_exp_f32_e32 v181, v220
	v_min_f32_e32 v213, 0x42fc0000, v86
	v_min_f32_e32 v214, 0x42fc0000, v102
	v_min_f32_e32 v215, 0x42fc0000, v87
	v_min_f32_e32 v216, 0x42fc0000, v103
	v_exp_f32_e32 v148, v213
	v_exp_f32_e32 v170, v214
	v_exp_f32_e32 v149, v215
	v_exp_f32_e32 v171, v216
	v_min_f32_e32 v217, 0x42fc0000, v88
	v_min_f32_e32 v218, 0x42fc0000, v104
	v_min_f32_e32 v219, 0x42fc0000, v89
	v_min_f32_e32 v220, 0x42fc0000, v105
	v_exp_f32_e32 v168, v217
	v_exp_f32_e32 v182, v218
	v_exp_f32_e32 v169, v219
	v_exp_f32_e32 v183, v220
	v_min_f32_e32 v213, 0x42fc0000, v90
	v_min_f32_e32 v214, 0x42fc0000, v106
	v_min_f32_e32 v215, 0x42fc0000, v91
	v_min_f32_e32 v216, 0x42fc0000, v107
	v_exp_f32_e32 v150, v213
	v_exp_f32_e32 v172, v214
	v_exp_f32_e32 v151, v215
	v_exp_f32_e32 v173, v216
	v_min_f32_e32 v217, 0x42fc0000, v92
	v_min_f32_e32 v218, 0x42fc0000, v108
	v_min_f32_e32 v219, 0x42fc0000, v93
	v_min_f32_e32 v220, 0x42fc0000, v109
	v_exp_f32_e32 v106, v217
	v_exp_f32_e32 v184, v218
	v_exp_f32_e32 v107, v219
	v_exp_f32_e32 v185, v220
	v_min_f32_e32 v213, 0x42fc0000, v94
	v_min_f32_e32 v214, 0x42fc0000, v110
	v_min_f32_e32 v215, 0x42fc0000, v95
	v_min_f32_e32 v216, 0x42fc0000, v111
	v_exp_f32_e32 v108, v213
	v_exp_f32_e32 v176, v214
	v_exp_f32_e32 v109, v215
	v_exp_f32_e32 v177, v216
	v_min_f32_e32 v217, 0x42fc0000, v96
	v_min_f32_e32 v218, 0x42fc0000, v112
	v_min_f32_e32 v219, 0x42fc0000, v97
	v_min_f32_e32 v220, 0x42fc0000, v113
	v_exp_f32_e32 v110, v217
	v_exp_f32_e32 v174, v218
	v_exp_f32_e32 v111, v219
	v_exp_f32_e32 v175, v220
	v_add_f32_e32 v83, 1.0, v164
	v_add_f32_e32 v84, 1.0, v165
	v_add_f32_e32 v85, 1.0, v180
	v_add_f32_e32 v86, 1.0, v181
	v_add_f32_e32 v87, 1.0, v170
	v_add_f32_e32 v88, 1.0, v171
	v_add_f32_e32 v89, 1.0, v182
	v_add_f32_e32 v92, 1.0, v183
	v_add_f32_e32 v93, 1.0, v172
	v_add_f32_e32 v96, 1.0, v173
	v_add_f32_e32 v97, 1.0, v184
	v_add_f32_e32 v100, 1.0, v185
	v_add_f32_e32 v101, 1.0, v176
	v_add_f32_e32 v104, 1.0, v177
	v_add_f32_e32 v112, 1.0, v174
	v_add_f32_e32 v82, 1.0, v162
	v_rcp_f32_e32 v90, v83
	v_add_f32_e32 v83, 1.0, v163
	v_rcp_f32_e32 v91, v84
	v_add_f32_e32 v84, 1.0, v166
	v_rcp_f32_e32 v94, v85
	v_add_f32_e32 v85, 1.0, v167
	v_rcp_f32_e32 v95, v86
	v_add_f32_e32 v86, 1.0, v148
	v_rcp_f32_e32 v98, v87
	v_add_f32_e32 v87, 1.0, v149
	v_rcp_f32_e32 v99, v88
	v_add_f32_e32 v88, 1.0, v168
	v_rcp_f32_e32 v102, v89
	v_add_f32_e32 v89, 1.0, v169
	v_rcp_f32_e32 v103, v92
	v_add_f32_e32 v92, 1.0, v150
	v_rcp_f32_e32 v146, v93
	v_add_f32_e32 v93, 1.0, v151
	v_rcp_f32_e32 v147, v96
	v_add_f32_e32 v96, 1.0, v106
	v_rcp_f32_e32 v156, v97
	v_add_f32_e32 v97, 1.0, v107
	v_rcp_f32_e32 v157, v100
	v_add_f32_e32 v100, 1.0, v108
	v_rcp_f32_e32 v158, v101
	v_add_f32_e32 v101, 1.0, v109
	v_rcp_f32_e32 v159, v104
	v_add_f32_e32 v104, 1.0, v110
	v_add_f32_e32 v105, 1.0, v111
	v_rcp_f32_e32 v160, v112
	v_add_f32_e32 v112, 1.0, v175
	v_rcp_f32_e32 v82, v82
	v_rcp_f32_e32 v83, v83
	v_rcp_f32_e32 v84, v84
	v_rcp_f32_e32 v85, v85
	v_rcp_f32_e32 v86, v86
	v_rcp_f32_e32 v87, v87
	v_rcp_f32_e32 v88, v88
	v_rcp_f32_e32 v89, v89
	v_rcp_f32_e32 v92, v92
	v_rcp_f32_e32 v93, v93
	v_rcp_f32_e32 v96, v96
	v_rcp_f32_e32 v97, v97
	v_rcp_f32_e32 v100, v100
	v_rcp_f32_e32 v101, v101
	v_rcp_f32_e32 v104, v104
	v_rcp_f32_e32 v105, v105
	v_rcp_f32_e32 v161, v112
	v_pk_mul_f32 v[154:155], v[108:109], v[100:101]
	v_pk_mul_f32 v[112:113], v[106:107], v[96:97]
	v_pk_mul_f32 v[152:153], v[110:111], v[104:105]
	v_pk_mul_f32 v[150:151], v[150:151], v[92:93]
	v_pk_mul_f32 v[110:111], v[168:169], v[88:89]
	v_pk_mul_f32 v[148:149], v[148:149], v[86:87]
	v_pk_mul_f32 v[106:107], v[166:167], v[84:85]
	v_pk_mul_f32 v[108:109], v[162:163], v[82:83]
	v_pk_mul_f32 v[174:175], v[174:175], v[160:161]
	v_pk_mul_f32 v[176:177], v[176:177], v[158:159]
	v_pk_mul_f32 v[168:169], v[184:185], v[156:157]
	v_pk_mul_f32 v[172:173], v[172:173], v[146:147]
	v_pk_mul_f32 v[166:167], v[182:183], v[102:103]
	v_pk_mul_f32 v[170:171], v[170:171], v[98:99]
	v_pk_mul_f32 v[162:163], v[180:181], v[94:95]
	v_pk_mul_f32 v[164:165], v[164:165], v[90:91]
	s_cbranch_scc1 .LBB0_932
	v_add_u32_e32 v180, 0x4000007b, v192
	s_brev_b32 s0, -4
	v_cmp_lt_u32_e32 vcc, s0, v180
	v_add_u32_e32 v180, 0x5b, v192
	v_cmp_gt_u32_e64 s[0:1], -2.0, v180
	v_add_u32_e32 v180, 0x7a, v192
	v_cmp_gt_u32_e64 s[44:45], -2.0, v180
	v_add_u32_e32 v180, 0x5a, v192
	v_cndmask_b32_e64 v90, v90, 0, s[0:1]
	v_cndmask_b32_e64 v164, v164, 1.0, s[0:1]
	v_cmp_gt_u32_e64 s[0:1], -2.0, v180
	v_add_u32_e32 v180, 0x79, v192
	v_cmp_gt_u32_e64 s[46:47], -2.0, v180
	v_add_u32_e32 v180, 0x59, v192
	v_cndmask_b32_e64 v91, v91, 0, s[0:1]
	v_cndmask_b32_e64 v165, v165, 1.0, s[0:1]
	v_cmp_gt_u32_e64 s[0:1], -2.0, v180
	v_add_u32_e32 v180, 0x78, v192
	v_cmp_gt_u32_e64 s[48:49], -2.0, v180
	v_add_u32_e32 v180, 0x58, v192
	v_cndmask_b32_e64 v94, v94, 0, s[0:1]
	v_cndmask_b32_e64 v162, v162, 1.0, s[0:1]
	v_cmp_gt_u32_e64 s[0:1], -2.0, v180
	v_add_u32_e32 v180, 0x73, v192
	v_cmp_gt_u32_e64 s[50:51], -2.0, v180
	v_add_u32_e32 v180, 0x53, v192
	v_cndmask_b32_e64 v95, v95, 0, s[0:1]
	v_cndmask_b32_e64 v163, v163, 1.0, s[0:1]
	v_cmp_gt_u32_e64 s[0:1], -2.0, v180
	v_add_u32_e32 v180, 0x72, v192
	v_cmp_gt_u32_e64 s[52:53], -2.0, v180
	v_add_u32_e32 v180, 0x52, v192
	v_cndmask_b32_e64 v98, v98, 0, s[0:1]
	v_cndmask_b32_e64 v170, v170, 1.0, s[0:1]
	v_cmp_gt_u32_e64 s[0:1], -2.0, v180
	v_add_u32_e32 v180, 0x71, v192
	v_cmp_gt_u32_e64 s[54:55], -2.0, v180
	v_add_u32_e32 v180, 0x51, v192
	v_cndmask_b32_e64 v99, v99, 0, s[0:1]
	v_cndmask_b32_e64 v171, v171, 1.0, s[0:1]
	v_cmp_gt_u32_e64 s[0:1], -2.0, v180
	v_add_u32_e32 v180, 0x70, v192
	s_nop 0
	v_cndmask_b32_e64 v102, v102, 0, s[0:1]
	v_cndmask_b32_e64 v166, v166, 1.0, s[0:1]
	v_cmp_gt_u32_e64 s[0:1], -2.0, v180
	v_add_u32_e32 v180, 0x50, v192
	v_cmp_gt_u32_e64 s[58:59], -2.0, v180
	v_add_u32_e32 v180, 0x6b, v192
	s_nop 0
	v_cndmask_b32_e64 v103, v103, 0, s[58:59]
	v_cndmask_b32_e64 v167, v167, 1.0, s[58:59]
	v_cmp_gt_u32_e64 s[58:59], -2.0, v180
	v_add_u32_e32 v180, 0x4b, v192
	v_cmp_gt_u32_e64 s[60:61], -2.0, v180
	v_add_u32_e32 v180, 0x6a, v192
	s_nop 0
	v_cndmask_b32_e64 v146, v146, 0, s[60:61]
	v_cndmask_b32_e64 v172, v172, 1.0, s[60:61]
	v_cmp_gt_u32_e64 s[60:61], -2.0, v180
	v_add_u32_e32 v180, 0x4a, v192
	v_cmp_gt_u32_e64 s[62:63], -2.0, v180
	v_add_u32_e32 v180, 0x69, v192
	s_nop 0
	v_cndmask_b32_e64 v147, v147, 0, s[62:63]
	v_cndmask_b32_e64 v173, v173, 1.0, s[62:63]
	v_cmp_gt_u32_e64 s[62:63], -2.0, v180
	v_add_u32_e32 v180, 0x49, v192
	v_cmp_gt_u32_e64 s[64:65], -2.0, v180
	v_add_u32_e32 v180, 0x68, v192
	s_nop 0
	v_cndmask_b32_e64 v156, v156, 0, s[64:65]
	v_cndmask_b32_e64 v168, v168, 1.0, s[64:65]
	v_cmp_gt_u32_e64 s[64:65], -2.0, v180
	v_add_u32_e32 v180, 0x48, v192
	v_cmp_gt_u32_e64 s[66:67], -2.0, v180
	v_add_u32_e32 v180, 0x63, v192
	s_nop 0
	v_cndmask_b32_e64 v157, v157, 0, s[66:67]
	v_cndmask_b32_e64 v169, v169, 1.0, s[66:67]
	v_cmp_gt_u32_e64 s[66:67], -2.0, v180
	v_add_u32_e32 v180, 0x43, v192
	v_cmp_gt_u32_e64 s[68:69], -2.0, v180
	v_add_u32_e32 v180, 0x62, v192
	s_nop 0
	v_cndmask_b32_e64 v158, v158, 0, s[68:69]
	v_cndmask_b32_e64 v176, v176, 1.0, s[68:69]
	v_cmp_gt_u32_e64 s[68:69], -2.0, v180
	v_add_u32_e32 v180, 0x42, v192
	v_cmp_gt_u32_e64 s[70:71], -2.0, v180
	v_add_u32_e32 v180, 0x61, v192
	s_nop 0
	v_cndmask_b32_e64 v159, v159, 0, s[70:71]
	v_cndmask_b32_e64 v177, v177, 1.0, s[70:71]
	v_cmp_gt_u32_e64 s[70:71], -2.0, v180
	v_add_u32_e32 v180, 0x41, v192
	v_cmp_gt_u32_e64 s[72:73], -2.0, v180
	v_add_u32_e32 v180, 0x60, v192
	s_nop 0
	v_cndmask_b32_e64 v160, v160, 0, s[72:73]
	v_cndmask_b32_e64 v174, v174, 1.0, s[72:73]
	v_cmp_gt_u32_e64 s[72:73], -2.0, v180
	v_add_u32_e32 v180, 64, v192
	v_cmp_gt_u32_e64 s[76:77], -2.0, v180
	s_and_saveexec_b64 s[18:19], s[76:77]
	s_mov_b32 s76, 1.0
	v_mov_b32_e32 v175, s76
	v_mov_b32_e32 v161, 0
	s_or_b64 exec, exec, s[18:19]
	v_cndmask_b32_e64 v82, v82, 0, vcc
	v_cndmask_b32_e64 v108, v108, 1.0, vcc
	v_cndmask_b32_e64 v83, v83, 0, s[44:45]
	v_cndmask_b32_e64 v109, v109, 1.0, s[44:45]
	v_cndmask_b32_e64 v84, v84, 0, s[46:47]
	v_cndmask_b32_e64 v106, v106, 1.0, s[46:47]
	v_cndmask_b32_e64 v85, v85, 0, s[48:49]
	v_cndmask_b32_e64 v107, v107, 1.0, s[48:49]
	v_cndmask_b32_e64 v86, v86, 0, s[50:51]
	v_cndmask_b32_e64 v148, v148, 1.0, s[50:51]
	v_cndmask_b32_e64 v87, v87, 0, s[52:53]
	v_cndmask_b32_e64 v149, v149, 1.0, s[52:53]
	v_cndmask_b32_e64 v88, v88, 0, s[54:55]
	v_cndmask_b32_e64 v110, v110, 1.0, s[54:55]
	v_cndmask_b32_e64 v89, v89, 0, s[0:1]
	v_cndmask_b32_e64 v111, v111, 1.0, s[0:1]
	v_cndmask_b32_e64 v92, v92, 0, s[58:59]
	v_cndmask_b32_e64 v150, v150, 1.0, s[58:59]
	v_cndmask_b32_e64 v93, v93, 0, s[60:61]
	v_cndmask_b32_e64 v151, v151, 1.0, s[60:61]
	v_cndmask_b32_e64 v96, v96, 0, s[62:63]
	v_cndmask_b32_e64 v112, v112, 1.0, s[62:63]
	v_cndmask_b32_e64 v97, v97, 0, s[64:65]
	v_cndmask_b32_e64 v113, v113, 1.0, s[64:65]
	v_cndmask_b32_e64 v100, v100, 0, s[66:67]
	v_cndmask_b32_e64 v154, v154, 1.0, s[66:67]
	v_cndmask_b32_e64 v101, v101, 0, s[68:69]
	v_cndmask_b32_e64 v155, v155, 1.0, s[68:69]
	v_cndmask_b32_e64 v104, v104, 0, s[70:71]
	v_cndmask_b32_e64 v152, v152, 1.0, s[70:71]
	v_cndmask_b32_e64 v105, v105, 0, s[72:73]
	v_cndmask_b32_e64 v153, v153, 1.0, s[72:73]
	v_readlane_b32 s48, v254, 46
